# prompt-scan workgroups run at wave priority 3 (s_setprio) so the co-resident sample-unit / weight-transpose workgroups do not steal VALU issue slots from the sequential scan
# speedup vs baseline: 1.0534x; 1.0053x over previous
.LBB0_400:
	s_or_b64 exec, exec, s[4:5]
	s_waitcnt lgkmcnt(0)
	s_barrier
	s_load_dword s84, s[88:89], 0x108
	s_add_u32 s0, s88, 0x108
	s_addc_u32 s1, s89, 0
	v_writelane_b32 v238, s0, 38
	s_cmpk_gt_i32 s2, 0xff
	s_nop 0
	v_writelane_b32 v238, s1, 39
	s_cbranch_scc1 .LBB0_446
	s_setprio 3
	s_add_u32 s44, s30, 0xfad4000
	s_movk_i32 s3, 0x100
	s_addc_u32 s45, s31, 0
	v_cmp_gt_u32_e64 s[4:5], s3, v153
	s_add_u32 s3, s30, 0xf9d4000
	s_addc_u32 s10, s31, 0
	v_lshlrev_b32_e32 v99, 7, v158
	s_waitcnt vmcnt(1)
	v_mul_u32_u24_e32 v0, 0x380, v158
	v_lshlrev_b32_e32 v104, 6, v159
	s_add_u32 s11, s28, 0x2140000
	v_lshlrev_b32_e32 v36, 2, v159
	v_add3_u32 v105, v99, v0, v104
	s_addc_u32 s33, s29, 0
	v_mov_b32_e32 v0, 0x5080
	v_cmp_lt_u32_e32 vcc, 15, v153
	v_lshl_or_b32 v39, v158, 6, v36
	v_and_b32_e32 v100, 28, v157
	s_add_u32 s34, s28, 0x4200000
	v_lshl_add_u32 v110, v158, 3, v0
	v_mov_b32_e32 v0, 0x100
	v_lshlrev_b32_e32 v37, 1, v158
	v_cndmask_b32_e64 v38, 0, 1, vcc
	s_mov_b32 s43, 0
	v_cmp_gt_u32_e64 s[0:1], 16, v153
	v_lshlrev_b32_e32 v41, 2, v39
	v_bfe_u32 v98, v153, 3, 1
	v_lshl_or_b32 v101, v100, 2, v99
	v_add_u32_e32 v102, 48, v158
	v_lshlrev_b32_e32 v103, 10, v158
	v_lshlrev_b32_e32 v40, 1, v159
	v_mov_b32_e32 v43, 0
	v_sub_u32_e32 v106, 0x810, v158
	v_add_u32_e32 v107, 0x50, v158
	v_or_b32_e32 v108, 0x800, v158
	s_addc_u32 s35, s29, 0
	v_or_b32_e32 v109, 0xb000, v157
	v_lshl_or_b32 v111, v159, 4, v0
	s_movk_i32 s85, 0x1800
	v_mov_b64_e32 v[44:45], s[60:61]
	s_movk_i32 s86, 0x1000
	s_movk_i32 s87, 0x4080
	s_movk_i32 s88, 0x5800
	s_mov_b32 s89, s2
	s_branch .LBB0_403

.LBB0_446:
	s_setprio 0
	s_waitcnt lgkmcnt(0)
	s_cmpk_gt_i32 s84, 0x100
	s_mov_b64 s[0:1], -1
	s_cbranch_scc1 .LBB0_595
	s_cmpk_gt_i32 s2, 0xfff
	s_cbranch_scc1 .LBB0_516
	s_add_u32 s54, s30, 0xfad4000
	s_movk_i32 s3, 0x100
	s_addc_u32 s55, s31, 0
	v_cmp_gt_u32_e64 s[4:5], s3, v153
	s_add_u32 s3, s30, 0xf9d4000
	s_addc_u32 s33, s31, 0
	v_lshlrev_b32_e32 v103, 7, v158
	s_waitcnt vmcnt(1)
	v_mul_u32_u24_e32 v0, 0x380, v158
	v_lshlrev_b32_e32 v108, 6, v159
	s_add_u32 s85, s28, 0x2140000
	v_lshlrev_b32_e32 v36, 2, v159
	v_add3_u32 v109, v103, v0, v108
	s_addc_u32 s86, s29, 0
	v_mov_b32_e32 v0, 0x5080
	v_cmp_lt_u32_e32 vcc, 15, v153
	v_lshl_or_b32 v41, v158, 6, v36
	v_and_b32_e32 v104, 28, v157
	s_add_u32 s80, s28, 0x4200000
	v_lshl_add_u32 v111, v158, 3, v0
	v_mov_b32_e32 v0, 0x100
	v_lshlrev_b32_e32 v37, 1, v158
	s_mov_b32 s43, 0
	v_mov_b32_e32 v39, 0
	v_cndmask_b32_e64 v40, 0, 1, vcc
	v_cmp_gt_u32_e64 s[0:1], 16, v153
	v_lshlrev_b32_e32 v43, 2, v41
	v_bfe_u32 v102, v153, 3, 1
	v_lshl_or_b32 v105, v104, 2, v103
	v_add_u32_e32 v106, 48, v158
	v_lshlrev_b32_e32 v107, 10, v158
	v_lshlrev_b32_e32 v42, 1, v159
	s_addc_u32 s81, s29, 0
	v_or_b32_e32 v110, 0xb000, v157
	v_lshl_or_b32 v112, v159, 4, v0
	s_movk_i32 s89, 0x1800
	v_mov_b64_e32 v[44:45], s[60:61]
	s_movk_i32 s91, 0x4080
	s_movk_i32 s92, 0x5800
	v_lshlrev_b32_e32 v46, 2, v36
	s_mov_b32 s93, s2
	s_branch .LBB0_450
